# V13 + tile order WGM 8->4 for the two FFN-up GEMMs (4 M-tiles x 8 N-tiles per XCD round: A tiles stay L2-resident across rounds)
# speedup vs baseline: 1.0085x; 1.0013x over previous
; #define PG8_BAR __builtin_amdgcn_s_barrier()
;     __host__ __device__ bool next(int i, Unit& u) const {
;         const long L = (long)i * G + c; if (L >= nwg) return false;
;         int wgid = (int)L; { const int q = nwg / NXCD, r = nwg % NXCD, xcd = wgid % NXCD, off = wgid / NXCD; wgid = (xcd < r ? xcd * (q + 1) : r * (q + 1) + (xcd - r) * q) + off; }
;         const int nig = WGM * nN, gid = wgid / nig, fm = gid * WGM, gsz = (nM - fm) < WGM ? (nM - fm) : WGM;
;         u.pm = fm + ((wgid % nig) % gsz); u.pn = (wgid % nig) / gsz; u.ord = i; return true;
; template <class Epi, class Sched, bool ALIGN_EPI = false, bool SP2 = false>
; __device__ __forceinline__ void gemm_phase(PG8_LAS unsigned char* lds, const Gemm g, const Sched& S, const Epi& E, int tid_in) {
;     ...
;     const int tid = tid_, wid = __builtin_amdgcn_readfirstlane(tid >> 6), lane = tid & 63, wr = wid >> 2, wc = wid & 3, fr = lane & 15, fq = lane >> 4;
;     const int K = g.K, nt = K / BK;
;     unsigned voffA[2], voffB[2];
; #pragma unroll
;     for (int i = 0; i < 2; ++i) { int R, C; stage_rc(tid * 16 + i * 8192, R, C); const int Rb = Epi::PERM ? ((R & ~31) + perm32(R & 31)) : R;
;         voffA[i] = (unsigned)(R * K + C) * 2u; voffB[i] = (unsigned)(Rb * K + C) * 2u; }
;     const size_t kstep = (size_t)(BK * 2);
;     const size_t hstep = (size_t)HALF * K * 2;
;     const size_t tstep = 2 * hstep;
;     const unsigned ldsw = (unsigned)wid * 1024u;
;     const int aoff = lds_byte(wr * 64 + fr, fq * 8), boff = lds_byte(wc * 32 + fr, fq * 8);
;     ...
;     Unit cur, nxt; int ui = 0;
;     if (!S.next(0, cur)) return;
;     f32x4 acc[2][2][4][2];
; #pragma unroll
;     for (int a = 0; a < 2; ++a)
; #pragma unroll
;         for (int b = 0; b < 2; ++b)
; #pragma unroll
;             for (int m = 0; m < 4; ++m)
; #pragma unroll
;                 for (int n = 0; n < 2; ++n) acc[a][b][m][n] = (f32x4){0.f, 0.f, 0.f, 0.f};
;     bf16x8 At[4][2], B0[2][2], B1[2][2];
;     const char* cA = (const char*)g.A + (size_t)cur.pm * tstep; const char* cB = (const char*)g.Bt + (size_t)cur.pn * tstep;
;     S.a_ready(cur);
;     if constexpr (SP2) {
;         PG8_STAGE(PG8_SB(0, 0), cB, voffB); PG8_STAGE(PG8_SB(0, 1), cB + hstep, voffB); PG8_STAGE(PG8_SA(0, 0), cA, voffA); PG8_STAGE(PG8_SA(0, 1), cA + hstep, voffA);
;         if (wr == 1) PG8_BAR;
.LBB0_366:
	s_cmp_lt_i32 s42, 2
	s_cselect_b64 s[0:1], -1, 0
	s_and_b64 s[4:5], s[0:1], s[2:3]
	s_andn2_b64 vcc, exec, s[4:5]
	s_cbranch_vccnz .LBB0_383
	v_mbcnt_hi_u32_b32 v0, -1, v230
	v_readlane_b32 s0, v248, 0
	s_cmpk_gt_i32 s33, 0xaff
	s_nop 0
	v_add_u32_e32 v9, s0, v0
	s_nop 0
	v_readfirstlane_b32 s3, v9
	s_cbranch_scc1 .LBB0_383
	v_lshlrev_b32_e32 v0, 4, v9
	v_add_u32_e32 v1, 0x2000, v0
	v_ashrrev_i32_e32 v2, 31, v1
	v_lshrrev_b32_e32 v2, 22, v2
	v_add_u32_e32 v2, v1, v2
	v_ashrrev_i32_e32 v8, 10, v2
	v_mul_i32_i24_e32 v2, 0x400, v8
	v_sub_u32_e32 v1, v1, v2
	v_lshrrev_b32_e32 v2, 4, v1
	v_bitop3_b32 v1, v2, v1, 32 bitop3:0x6c
	v_ashrrev_i32_e32 v2, 31, v1
	v_lshrrev_b32_e32 v2, 26, v2
	v_add_u32_e32 v2, v1, v2
	v_lshlrev_b32_e32 v3, 3, v8
	v_ashrrev_i32_e32 v10, 6, v2
	v_and_b32_e32 v3, -16, v3
	v_add_u32_e32 v3, v10, v3
	v_and_b32_e32 v4, 3, v10
	s_mov_b32 s2, 0x1fffe0
	s_waitcnt lgkmcnt(0)
	v_lshrrev_b32_e32 v5, 2, v3
	v_lshlrev_b32_e32 v6, 1, v3
	v_and_b32_e32 v2, 0xc0, v2
	v_and_or_b32 v4, v3, s2, v4
	v_and_b32_e32 v5, 4, v5
	v_and_b32_e32 v6, 24, v6
	v_sub_u32_e32 v1, v1, v2
	v_mov_b32_e32 v2, 1
	v_or3_b32 v4, v4, v5, v6
	v_lshlrev_b32_e32 v5, 5, v8
	v_ashrrev_i16_sdwa v1, v2, sext(v1) dst_sel:DWORD dst_unused:UNUSED_PAD src0_sel:DWORD src1_sel:BYTE_0
	v_and_b32_e32 v5, 32, v5
	v_bfe_i32 v11, v1, 0, 16
	v_add_lshl_u32 v1, v5, v11, 1
	v_lshl_add_u32 v128, v4, 11, v1
	v_lshl_add_u32 v130, v3, 11, v1
	v_bfe_i32 v1, v9, 27, 1
	v_lshrrev_b32_e32 v1, 22, v1
	v_add_u32_e32 v1, v0, v1
	v_and_b32_e32 v1, 0xfffffc00, v1
	v_sub_u32_e32 v0, v0, v1
	v_lshrrev_b32_e32 v1, 4, v0
	v_ashrrev_i32_e32 v3, 31, v9
	v_bitop3_b32 v0, v1, v0, 32 bitop3:0x6c
	v_lshrrev_b32_e32 v3, 26, v3
	v_ashrrev_i32_e32 v1, 31, v0
	v_add_u32_e32 v3, v9, v3
	s_add_u32 s0, s40, 0x3a00000
	v_lshrrev_b32_e32 v1, 26, v1
	v_ashrrev_i32_e32 v13, 6, v3
	s_addc_u32 s1, s41, 0
	v_add_u32_e32 v1, v0, v1
	v_lshlrev_b32_e32 v3, 3, v13
	s_add_u32 s30, s40, 0x100000
	v_ashrrev_i32_e32 v12, 6, v1
	v_and_b32_e32 v3, -16, v3
	s_addc_u32 s31, s41, 0
	v_add_u32_e32 v3, v12, v3
	v_and_b32_e32 v4, 3, v12
	s_ashr_i32 s35, s33, 31
	v_and_or_b32 v4, v3, s2, v4
	s_lshr_b32 s2, s35, 29
	s_add_i32 s2, s33, s2
	s_ashr_i32 s10, s3, 6
	s_ashr_i32 s6, s2, 3
	s_and_b32 s2, s2, -8
	s_ashr_i32 s12, s3, 8
	s_lshl_b32 s34, s10, 10
	s_sub_i32 s2, s33, s2
	s_cmp_lt_i32 s2, 0
	s_movk_i32 s36, 0x161
	s_cselect_b32 s7, s36, 0x160
	s_mul_i32 s2, s2, s7
	s_add_i32 s2, s2, s6
	s_mul_hi_i32 s6, s2, 0x2e8ba2e9
	s_lshr_b32 s7, s6, 31
	s_ashr_i32 s6, s6, 4
	s_add_i32 s6, s6, s7
	s_lshl_b32 s7, s6, 2
	s_mulk_i32 s6, 0x58
	s_sub_i32 s6, s2, s6
	s_sext_i32_i16 s2, s6
	s_bfe_u32 s2, s2, 0x2001c
	s_add_i32 s8, s6, s2
	s_sext_i32_i16 s2, s8
	s_and_b32 s8, s8, 0xfffc
	s_sub_i32 s6, s6, s8
	s_sext_i32_i16 s6, s6
	v_lshrrev_b32_e32 v5, 2, v3
	v_lshlrev_b32_e32 v6, 1, v3
	v_and_b32_e32 v1, 0xc0, v1
	s_lshr_b32 s2, s2, 2
	s_add_i32 s22, s7, s6
	v_and_b32_e32 v5, 4, v5
	v_and_b32_e32 v6, 24, v6
	v_sub_u32_e32 v0, v0, v1
	s_ashr_i32 s23, s22, 31
	s_bfe_i64 s[8:9], s[2:3], 0x100000
	v_or3_b32 v4, v4, v5, v6
	v_lshlrev_b32_e32 v5, 5, v13
	v_ashrrev_i16_sdwa v0, v2, sext(v0) dst_sel:DWORD dst_unused:UNUSED_PAD src0_sel:DWORD src1_sel:BYTE_0
	s_lshl_b64 s[6:7], s[22:23], 19
	s_lshl_b64 s[8:9], s[8:9], 19
	v_and_b32_e32 v5, 32, v5
	v_bfe_i32 v14, v0, 0, 16
	s_add_u32 s26, s30, s8
	v_add_lshl_u32 v0, v5, v14, 1
	s_addc_u32 s27, s31, s9
	s_add_i32 s23, s34, 0
	v_lshl_add_u32 v132, v4, 11, v0
	s_add_i32 m0, s23, 0x10000
	v_lshl_add_u32 v134, v3, 11, v0
	global_load_lds_dwordx4 v132, s[26:27]
	s_add_i32 m0, s23, 0x12000
	s_add_u32 s8, s26, 0x40000
	global_load_lds_dwordx4 v128, s[26:27]
	s_addc_u32 s9, s27, 0
	s_add_i32 m0, s23, 0x14000
	v_mov_b32_e32 v133, 0
	global_load_lds_dwordx4 v132, s[8:9]
	s_add_i32 m0, s23, 0x16000
	s_add_u32 s24, s0, s6
	s_addc_u32 s25, s1, s7
	s_add_i32 s37, s23, 0x2000
	global_load_lds_dwordx4 v128, s[8:9]
	s_mov_b32 m0, s23
	s_add_u32 s6, s24, 0x40000
	global_load_lds_dwordx4 v134, s[24:25]
	s_mov_b32 m0, s37
	s_addc_u32 s7, s25, 0
	s_add_i32 s38, s23, 0x4000
	global_load_lds_dwordx4 v130, s[24:25]
	s_mov_b32 m0, s38
	s_add_i32 s39, s23, 0x6000
	global_load_lds_dwordx4 v134, s[6:7]
	s_mov_b32 m0, s39
	v_mov_b32_e32 v129, v133
	global_load_lds_dwordx4 v130, s[6:7]
	v_mov_b32_e32 v135, v133
	v_mov_b32_e32 v131, v133
	s_cmp_eq_u32 s12, 1
	v_lshl_add_u64 v[6:7], s[26:27], 0, v[132:133]
	v_lshl_add_u64 v[4:5], s[26:27], 0, v[128:129]
	v_lshl_add_u64 v[0:1], s[24:25], 0, v[134:135]
	s_cselect_b64 s[6:7], -1, 0
	s_cmp_lg_u32 s12, 1
	v_lshl_add_u64 v[2:3], s[24:25], 0, v[130:131]
	s_cbranch_scc1 .LBB0_370
	s_barrier

;     __host__ __device__ bool next(int i, Unit& u) const {
;         const long L = (long)i * G + c; if (L >= nwg) return false;
;         int wgid = (int)L; { const int q = nwg / NXCD, r = nwg % NXCD, xcd = wgid % NXCD, off = wgid / NXCD; wgid = (xcd < r ? xcd * (q + 1) : r * (q + 1) + (xcd - r) * q) + off; }
;         const int nig = WGM * nN, gid = wgid / nig, fm = gid * WGM, gsz = (nM - fm) < WGM ? (nM - fm) : WGM;
;         u.pm = fm + ((wgid % nig) % gsz); u.pn = (wgid % nig) / gsz; u.ord = i; return true;
; template <class Epi, class Sched, bool ALIGN_EPI = false, bool SP2 = false>
; __device__ __forceinline__ void gemm_phase(PG8_LAS unsigned char* lds, const Gemm g, const Sched& S, const Epi& E, int tid_in) {
;     ...
;         const bool has_next = S.next(ui + 1, nxt);
;         const char* nA = has_next ? (const char*)g.A + (size_t)nxt.pm * tstep : cA; const char* nB = has_next ? (const char*)g.Bt + (size_t)nxt.pn * tstep : cB;
.LBB0_373:
	s_add_i32 s46, s46, 1
	s_mul_i32 s2, s46, s47
	s_mul_hi_u32 s3, s46, s66
	s_add_i32 s3, s3, s2
	s_mul_i32 s2, s46, s66
	s_add_u32 s18, s2, s33
	s_addc_u32 s19, s3, s35
	v_cmp_gt_i64_e32 vcc, s[18:19], v[142:143]
	v_cmp_lt_i64_e64 s[2:3], s[18:19], v[140:141]
	s_cbranch_vccnz .LBB0_375
	s_ashr_i32 s14, s18, 31
	s_lshr_b32 s14, s14, 29
	s_add_i32 s14, s18, s14
	s_ashr_i32 s15, s14, 3
	s_and_b32 s14, s14, -8
	s_sub_i32 s14, s18, s14
	s_cmp_lt_i32 s14, 0
	s_cselect_b32 s16, s36, 0x160
	s_mul_i32 s14, s14, s16
	s_add_i32 s14, s14, s15
	s_mul_hi_i32 s15, s14, 0x2e8ba2e9
	s_lshr_b32 s16, s15, 31
	s_ashr_i32 s15, s15, 4
	s_add_i32 s15, s15, s16
	s_lshl_b32 s16, s15, 2
	s_sub_i32 s17, 0x80, s16
	s_min_i32 s17, s17, 4
	s_abs_i32 s18, s17
	v_cvt_f32_u32_e32 v0, s18
	s_sub_i32 s20, 0, s18
	s_mulk_i32 s15, 0x58
	s_sub_i32 s15, s14, s15
	v_rcp_iflag_f32_e32 v0, v0
	s_abs_i32 s14, s15
	s_xor_b32 s19, s15, s17
	s_ashr_i32 s19, s19, 31
	v_mul_f32_e32 v0, 0x4f7ffffe, v0
	v_cvt_u32_f32_e32 v0, v0
	s_nop 0
	v_readfirstlane_b32 s21, v0
	s_mul_i32 s20, s20, s21
	s_mul_hi_u32 s20, s21, s20
	s_add_i32 s21, s21, s20
	s_mul_hi_u32 s20, s14, s21
	s_mul_i32 s21, s20, s18
	s_sub_i32 s14, s14, s21
	s_add_i32 s28, s20, 1
	s_sub_i32 s21, s14, s18
	s_cmp_ge_u32 s14, s18
	s_cselect_b32 s20, s28, s20
	s_cselect_b32 s14, s21, s14
	s_add_i32 s21, s20, 1
	s_cmp_ge_u32 s14, s18
	s_cselect_b32 s14, s21, s20
	s_xor_b32 s14, s14, s19
	s_sub_i32 s14, s14, s19
	s_mul_i32 s17, s14, s17
	s_sub_i32 s15, s15, s17
	s_add_i32 s16, s16, s15

.LBB0_1225:
	s_cmp_lt_i32 s42, 10
	s_cselect_b64 s[0:1], -1, 0
	s_and_b64 s[4:5], s[0:1], s[2:3]
	s_andn2_b64 vcc, exec, s[4:5]
	s_cbranch_vccnz .LBB0_1245
	v_mbcnt_hi_u32_b32 v0, -1, v230
	v_readlane_b32 s0, v248, 0
	s_sub_i32 s1, s66, s33
	s_add_i32 s2, s1, 0xaff
	v_add_u32_e32 v8, s0, v0
	s_abs_i32 s0, s66
	s_waitcnt lgkmcnt(0)
	v_cvt_f32_u32_e32 v1, s0
	s_sub_i32 s1, 0xfffff501, s1
	s_xor_b32 s3, s2, s66
	s_max_i32 s1, s2, s1
	v_rcp_iflag_f32_e32 v1, v1
	s_sub_i32 s2, 0, s0
	s_ashr_i32 s3, s3, 31
	v_mov_b32_e32 v0, v8
	v_mul_f32_e32 v1, 0x4f7ffffe, v1
	v_cvt_u32_f32_e32 v1, v1
	s_nop 0
	v_readfirstlane_b32 s6, v1
	s_mul_i32 s2, s2, s6
	s_mul_hi_u32 s2, s6, s2
	s_add_i32 s6, s6, s2
	s_mul_hi_u32 s2, s1, s6
	s_mul_i32 s6, s2, s0
	s_sub_i32 s1, s1, s6
	s_add_i32 s6, s2, 1
	s_sub_i32 s7, s1, s0
	s_cmp_ge_u32 s1, s0
	s_cselect_b32 s2, s6, s2
	s_cselect_b32 s1, s7, s1
	s_add_i32 s6, s2, 1
	s_cmp_ge_u32 s1, s0
	s_cselect_b32 s0, s6, s2
	s_xor_b32 s0, s0, s3
	s_sub_i32 s0, s0, s3
	s_lshl_b32 s0, s0, 8
	v_cmp_gt_i32_e32 vcc, s0, v0
	s_and_saveexec_b64 s[2:3], vcc
	s_cbranch_execz .LBB0_1229
	s_add_u32 s6, s40, 0x3400000
	v_lshl_add_u32 v2, v0, 2, 0
	s_addc_u32 s7, s41, 0
	v_and_b32_e32 v1, 0xff, v0
	v_add_u32_e32 v2, 0x20100, v2
	s_mov_b64 s[8:9], 0
	v_mov_b32_e32 v3, 0x160
	v_mov_b32_e32 v4, 0x161
	s_mov_b32 s1, 0x2e8ba2e9
	s_movk_i32 s10, 0x58
	v_mov_b32_e32 v5, 0x358637bd
	s_mov_b64 s[14:15], 0
	s_mov_b64 s[16:17], 0
	s_mov_b64 s[22:23], 0
	s_mov_b64 s[24:25], 0
	s_mov_b64 s[26:27], 0
	s_mov_b64 s[98:99], 0
	v_mov_b32_e32 v122, v2
	s_mov_b64 s[14:15], exec
	v_ashrrev_i32_e32 v6, 8, v0
	v_mul_lo_u32 v6, v6, s66
	v_add_u32_e32 v7, s33, v6
	v_ashrrev_i32_e32 v6, 31, v7
	v_lshrrev_b32_e32 v6, 29, v6
	v_add_u32_e32 v9, v7, v6
	v_ashrrev_i32_e32 v6, 3, v9
	v_and_b32_e32 v9, -8, v9
	v_sub_u32_e32 v7, v7, v9
	v_cmp_gt_i32_e32 vcc, 0, v7
	v_add_u32_e32 v0, 0x200, v0
	s_nop 0
	v_cndmask_b32_e32 v9, v3, v4, vcc
	v_mad_u64_u32 v[6:7], s[12:13], v7, v9, v[6:7]
	v_mul_hi_i32 v7, v6, s1
	v_lshrrev_b32_e32 v9, 31, v7
	v_ashrrev_i32_e32 v7, 4, v7
	v_add_u32_e32 v7, v7, v9
	v_lshlrev_b32_e32 v9, 2, v7
	v_mul_lo_u32 v7, v7, s10
	v_sub_u32_e32 v10, 0x80, v9
	v_sub_u32_e32 v6, v6, v7
	v_min_i32_e32 v7, 4, v10
	v_sub_u32_e32 v11, 0, v6
	v_ashrrev_i32_e32 v10, 31, v6
	v_max_i32_e32 v6, v6, v11
	v_sub_u32_e32 v11, 0, v7
	v_max_i32_e32 v7, v7, v11
	v_cvt_f32_u32_e32 v11, v7
	v_sub_u32_e32 v12, 0, v7
	v_rcp_iflag_f32_e32 v11, v11
	s_nop 0
	v_mul_f32_e32 v11, 0x4f7ffffe, v11
	v_cvt_u32_f32_e32 v11, v11
	v_mul_lo_u32 v12, v12, v11
	v_mul_hi_u32 v12, v11, v12
	v_add_u32_e32 v11, v11, v12
	v_mul_hi_u32 v11, v6, v11
	v_mul_lo_u32 v11, v11, v7
	v_sub_u32_e32 v6, v6, v11
	v_sub_u32_e32 v11, v6, v7
	v_cmp_ge_u32_e32 vcc, v6, v7
	s_nop 1
	v_cndmask_b32_e32 v6, v6, v11, vcc
	v_sub_u32_e32 v11, v6, v7
	v_cmp_ge_u32_e32 vcc, v6, v7
	s_nop 1
	v_cndmask_b32_e32 v6, v6, v11, vcc
	v_xor_b32_e32 v6, v6, v10
	v_sub_u32_e32 v6, v6, v10
	v_add_u32_e32 v6, v9, v6
	v_lshl_or_b32 v6, v6, 8, v1
	v_ashrrev_i32_e32 v7, 31, v6
	v_lshlrev_b64 v[6:7], 6, v[6:7]
	v_lshl_add_u64 v[6:7], s[6:7], 0, v[6:7]
	global_load_dwordx4 v[26:29], v[6:7], off
	global_load_dwordx4 v[30:33], v[6:7], off offset:32
	global_load_dwordx4 v[34:37], v[6:7], off offset:16
	global_load_dwordx4 v[38:41], v[6:7], off offset:48
	v_cmp_le_i32_e32 vcc, s0, v0
	s_or_b64 s[8:9], vcc, s[8:9]
	s_andn2_b64 exec, exec, s[8:9]
	s_cbranch_execz .Lfrs_wait_p9
	s_mov_b64 s[16:17], exec
	v_ashrrev_i32_e32 v6, 8, v0
	v_mul_lo_u32 v6, v6, s66
	v_add_u32_e32 v7, s33, v6
	v_ashrrev_i32_e32 v6, 31, v7
	v_lshrrev_b32_e32 v6, 29, v6
	v_add_u32_e32 v9, v7, v6
	v_ashrrev_i32_e32 v6, 3, v9
	v_and_b32_e32 v9, -8, v9
	v_sub_u32_e32 v7, v7, v9
	v_cmp_gt_i32_e32 vcc, 0, v7
	v_add_u32_e32 v0, 0x200, v0
	s_nop 0
	v_cndmask_b32_e32 v9, v3, v4, vcc
	v_mad_u64_u32 v[6:7], s[12:13], v7, v9, v[6:7]
	v_mul_hi_i32 v7, v6, s1
	v_lshrrev_b32_e32 v9, 31, v7
	v_ashrrev_i32_e32 v7, 4, v7
	v_add_u32_e32 v7, v7, v9
	v_lshlrev_b32_e32 v9, 2, v7
	v_mul_lo_u32 v7, v7, s10
	v_sub_u32_e32 v10, 0x80, v9
	v_sub_u32_e32 v6, v6, v7
	v_min_i32_e32 v7, 4, v10
	v_sub_u32_e32 v11, 0, v6
	v_ashrrev_i32_e32 v10, 31, v6
	v_max_i32_e32 v6, v6, v11
	v_sub_u32_e32 v11, 0, v7
	v_max_i32_e32 v7, v7, v11
	v_cvt_f32_u32_e32 v11, v7
	v_sub_u32_e32 v12, 0, v7
	v_rcp_iflag_f32_e32 v11, v11
	s_nop 0
	v_mul_f32_e32 v11, 0x4f7ffffe, v11
	v_cvt_u32_f32_e32 v11, v11
	v_mul_lo_u32 v12, v12, v11
	v_mul_hi_u32 v12, v11, v12
	v_add_u32_e32 v11, v11, v12
	v_mul_hi_u32 v11, v6, v11
	v_mul_lo_u32 v11, v11, v7
	v_sub_u32_e32 v6, v6, v11
	v_sub_u32_e32 v11, v6, v7
	v_cmp_ge_u32_e32 vcc, v6, v7
	s_nop 1
	v_cndmask_b32_e32 v6, v6, v11, vcc
	v_sub_u32_e32 v11, v6, v7
	v_cmp_ge_u32_e32 vcc, v6, v7
	s_nop 1
	v_cndmask_b32_e32 v6, v6, v11, vcc
	v_xor_b32_e32 v6, v6, v10
	v_sub_u32_e32 v6, v6, v10
	v_add_u32_e32 v6, v9, v6
	v_lshl_or_b32 v6, v6, 8, v1
	v_ashrrev_i32_e32 v7, 31, v6
	v_lshlrev_b64 v[6:7], 6, v[6:7]
	v_lshl_add_u64 v[6:7], s[6:7], 0, v[6:7]
	global_load_dwordx4 v[42:45], v[6:7], off
	global_load_dwordx4 v[46:49], v[6:7], off offset:32
	global_load_dwordx4 v[50:53], v[6:7], off offset:16
	global_load_dwordx4 v[54:57], v[6:7], off offset:48
	v_cmp_le_i32_e32 vcc, s0, v0
	s_or_b64 s[8:9], vcc, s[8:9]
	s_andn2_b64 exec, exec, s[8:9]
	s_cbranch_execz .Lfrs_wait_p9
	s_mov_b64 s[22:23], exec
	v_ashrrev_i32_e32 v6, 8, v0
	v_mul_lo_u32 v6, v6, s66
	v_add_u32_e32 v7, s33, v6
	v_ashrrev_i32_e32 v6, 31, v7
	v_lshrrev_b32_e32 v6, 29, v6
	v_add_u32_e32 v9, v7, v6
	v_ashrrev_i32_e32 v6, 3, v9
	v_and_b32_e32 v9, -8, v9
	v_sub_u32_e32 v7, v7, v9
	v_cmp_gt_i32_e32 vcc, 0, v7
	v_add_u32_e32 v0, 0x200, v0
	s_nop 0
	v_cndmask_b32_e32 v9, v3, v4, vcc
	v_mad_u64_u32 v[6:7], s[12:13], v7, v9, v[6:7]
	v_mul_hi_i32 v7, v6, s1
	v_lshrrev_b32_e32 v9, 31, v7
	v_ashrrev_i32_e32 v7, 4, v7
	v_add_u32_e32 v7, v7, v9
	v_lshlrev_b32_e32 v9, 2, v7
	v_mul_lo_u32 v7, v7, s10
	v_sub_u32_e32 v10, 0x80, v9
	v_sub_u32_e32 v6, v6, v7
	v_min_i32_e32 v7, 4, v10
	v_sub_u32_e32 v11, 0, v6
	v_ashrrev_i32_e32 v10, 31, v6
	v_max_i32_e32 v6, v6, v11
	v_sub_u32_e32 v11, 0, v7
	v_max_i32_e32 v7, v7, v11
	v_cvt_f32_u32_e32 v11, v7
	v_sub_u32_e32 v12, 0, v7
	v_rcp_iflag_f32_e32 v11, v11
	s_nop 0
	v_mul_f32_e32 v11, 0x4f7ffffe, v11
	v_cvt_u32_f32_e32 v11, v11
	v_mul_lo_u32 v12, v12, v11
	v_mul_hi_u32 v12, v11, v12
	v_add_u32_e32 v11, v11, v12
	v_mul_hi_u32 v11, v6, v11
	v_mul_lo_u32 v11, v11, v7
	v_sub_u32_e32 v6, v6, v11
	v_sub_u32_e32 v11, v6, v7
	v_cmp_ge_u32_e32 vcc, v6, v7
	s_nop 1
	v_cndmask_b32_e32 v6, v6, v11, vcc
	v_sub_u32_e32 v11, v6, v7
	v_cmp_ge_u32_e32 vcc, v6, v7
	s_nop 1
	v_cndmask_b32_e32 v6, v6, v11, vcc
	v_xor_b32_e32 v6, v6, v10
	v_sub_u32_e32 v6, v6, v10
	v_add_u32_e32 v6, v9, v6
	v_lshl_or_b32 v6, v6, 8, v1
	v_ashrrev_i32_e32 v7, 31, v6
	v_lshlrev_b64 v[6:7], 6, v[6:7]
	v_lshl_add_u64 v[6:7], s[6:7], 0, v[6:7]
	global_load_dwordx4 v[58:61], v[6:7], off
	global_load_dwordx4 v[62:65], v[6:7], off offset:32
	global_load_dwordx4 v[66:69], v[6:7], off offset:16
	global_load_dwordx4 v[70:73], v[6:7], off offset:48
	v_cmp_le_i32_e32 vcc, s0, v0
	s_or_b64 s[8:9], vcc, s[8:9]
	s_andn2_b64 exec, exec, s[8:9]
	s_cbranch_execz .Lfrs_wait_p9
	s_mov_b64 s[24:25], exec
	v_ashrrev_i32_e32 v6, 8, v0
	v_mul_lo_u32 v6, v6, s66
	v_add_u32_e32 v7, s33, v6
	v_ashrrev_i32_e32 v6, 31, v7
	v_lshrrev_b32_e32 v6, 29, v6
	v_add_u32_e32 v9, v7, v6
	v_ashrrev_i32_e32 v6, 3, v9
	v_and_b32_e32 v9, -8, v9
	v_sub_u32_e32 v7, v7, v9
	v_cmp_gt_i32_e32 vcc, 0, v7
	v_add_u32_e32 v0, 0x200, v0
	s_nop 0
	v_cndmask_b32_e32 v9, v3, v4, vcc
	v_mad_u64_u32 v[6:7], s[12:13], v7, v9, v[6:7]
	v_mul_hi_i32 v7, v6, s1
	v_lshrrev_b32_e32 v9, 31, v7
	v_ashrrev_i32_e32 v7, 4, v7
	v_add_u32_e32 v7, v7, v9
	v_lshlrev_b32_e32 v9, 2, v7
	v_mul_lo_u32 v7, v7, s10
	v_sub_u32_e32 v10, 0x80, v9
	v_sub_u32_e32 v6, v6, v7
	v_min_i32_e32 v7, 4, v10
	v_sub_u32_e32 v11, 0, v6
	v_ashrrev_i32_e32 v10, 31, v6
	v_max_i32_e32 v6, v6, v11
	v_sub_u32_e32 v11, 0, v7
	v_max_i32_e32 v7, v7, v11
	v_cvt_f32_u32_e32 v11, v7
	v_sub_u32_e32 v12, 0, v7
	v_rcp_iflag_f32_e32 v11, v11
	s_nop 0
	v_mul_f32_e32 v11, 0x4f7ffffe, v11
	v_cvt_u32_f32_e32 v11, v11
	v_mul_lo_u32 v12, v12, v11
	v_mul_hi_u32 v12, v11, v12
	v_add_u32_e32 v11, v11, v12
	v_mul_hi_u32 v11, v6, v11
	v_mul_lo_u32 v11, v11, v7
	v_sub_u32_e32 v6, v6, v11
	v_sub_u32_e32 v11, v6, v7
	v_cmp_ge_u32_e32 vcc, v6, v7
	s_nop 1
	v_cndmask_b32_e32 v6, v6, v11, vcc
	v_sub_u32_e32 v11, v6, v7
	v_cmp_ge_u32_e32 vcc, v6, v7
	s_nop 1
	v_cndmask_b32_e32 v6, v6, v11, vcc
	v_xor_b32_e32 v6, v6, v10
	v_sub_u32_e32 v6, v6, v10
	v_add_u32_e32 v6, v9, v6
	v_lshl_or_b32 v6, v6, 8, v1
	v_ashrrev_i32_e32 v7, 31, v6
	v_lshlrev_b64 v[6:7], 6, v[6:7]
	v_lshl_add_u64 v[6:7], s[6:7], 0, v[6:7]
	global_load_dwordx4 v[74:77], v[6:7], off
	global_load_dwordx4 v[78:81], v[6:7], off offset:32
	global_load_dwordx4 v[82:85], v[6:7], off offset:16
	global_load_dwordx4 v[86:89], v[6:7], off offset:48
	v_cmp_le_i32_e32 vcc, s0, v0
	s_or_b64 s[8:9], vcc, s[8:9]
	s_andn2_b64 exec, exec, s[8:9]
	s_cbranch_execz .Lfrs_wait_p9
	s_mov_b64 s[26:27], exec
	v_ashrrev_i32_e32 v6, 8, v0
	v_mul_lo_u32 v6, v6, s66
	v_add_u32_e32 v7, s33, v6
	v_ashrrev_i32_e32 v6, 31, v7
	v_lshrrev_b32_e32 v6, 29, v6
	v_add_u32_e32 v9, v7, v6
	v_ashrrev_i32_e32 v6, 3, v9
	v_and_b32_e32 v9, -8, v9
	v_sub_u32_e32 v7, v7, v9
	v_cmp_gt_i32_e32 vcc, 0, v7
	v_add_u32_e32 v0, 0x200, v0
	s_nop 0
	v_cndmask_b32_e32 v9, v3, v4, vcc
	v_mad_u64_u32 v[6:7], s[12:13], v7, v9, v[6:7]
	v_mul_hi_i32 v7, v6, s1
	v_lshrrev_b32_e32 v9, 31, v7
	v_ashrrev_i32_e32 v7, 4, v7
	v_add_u32_e32 v7, v7, v9
	v_lshlrev_b32_e32 v9, 2, v7
	v_mul_lo_u32 v7, v7, s10
	v_sub_u32_e32 v10, 0x80, v9
	v_sub_u32_e32 v6, v6, v7
	v_min_i32_e32 v7, 4, v10
	v_sub_u32_e32 v11, 0, v6
	v_ashrrev_i32_e32 v10, 31, v6
	v_max_i32_e32 v6, v6, v11
	v_sub_u32_e32 v11, 0, v7
	v_max_i32_e32 v7, v7, v11
	v_cvt_f32_u32_e32 v11, v7
	v_sub_u32_e32 v12, 0, v7
	v_rcp_iflag_f32_e32 v11, v11
	s_nop 0
	v_mul_f32_e32 v11, 0x4f7ffffe, v11
	v_cvt_u32_f32_e32 v11, v11
	v_mul_lo_u32 v12, v12, v11
	v_mul_hi_u32 v12, v11, v12
	v_add_u32_e32 v11, v11, v12
	v_mul_hi_u32 v11, v6, v11
	v_mul_lo_u32 v11, v11, v7
	v_sub_u32_e32 v6, v6, v11
	v_sub_u32_e32 v11, v6, v7
	v_cmp_ge_u32_e32 vcc, v6, v7
	s_nop 1
	v_cndmask_b32_e32 v6, v6, v11, vcc
	v_sub_u32_e32 v11, v6, v7
	v_cmp_ge_u32_e32 vcc, v6, v7
	s_nop 1
	v_cndmask_b32_e32 v6, v6, v11, vcc
	v_xor_b32_e32 v6, v6, v10
	v_sub_u32_e32 v6, v6, v10
	v_add_u32_e32 v6, v9, v6
	v_lshl_or_b32 v6, v6, 8, v1
	v_ashrrev_i32_e32 v7, 31, v6
	v_lshlrev_b64 v[6:7], 6, v[6:7]
	v_lshl_add_u64 v[6:7], s[6:7], 0, v[6:7]
	global_load_dwordx4 v[90:93], v[6:7], off
	global_load_dwordx4 v[94:97], v[6:7], off offset:32
	global_load_dwordx4 v[98:101], v[6:7], off offset:16
	global_load_dwordx4 v[102:105], v[6:7], off offset:48
	v_cmp_le_i32_e32 vcc, s0, v0
	s_or_b64 s[8:9], vcc, s[8:9]
	s_andn2_b64 exec, exec, s[8:9]
	s_cbranch_execz .Lfrs_wait_p9
	s_mov_b64 s[98:99], exec
	v_ashrrev_i32_e32 v6, 8, v0
	v_mul_lo_u32 v6, v6, s66
	v_add_u32_e32 v7, s33, v6
	v_ashrrev_i32_e32 v6, 31, v7
	v_lshrrev_b32_e32 v6, 29, v6
	v_add_u32_e32 v9, v7, v6
	v_ashrrev_i32_e32 v6, 3, v9
	v_and_b32_e32 v9, -8, v9
	v_sub_u32_e32 v7, v7, v9
	v_cmp_gt_i32_e32 vcc, 0, v7
	v_add_u32_e32 v0, 0x200, v0
	s_nop 0
	v_cndmask_b32_e32 v9, v3, v4, vcc
	v_mad_u64_u32 v[6:7], s[12:13], v7, v9, v[6:7]
	v_mul_hi_i32 v7, v6, s1
	v_lshrrev_b32_e32 v9, 31, v7
	v_ashrrev_i32_e32 v7, 4, v7
	v_add_u32_e32 v7, v7, v9
	v_lshlrev_b32_e32 v9, 2, v7
	v_mul_lo_u32 v7, v7, s10
	v_sub_u32_e32 v10, 0x80, v9
	v_sub_u32_e32 v6, v6, v7
	v_min_i32_e32 v7, 4, v10
	v_sub_u32_e32 v11, 0, v6
	v_ashrrev_i32_e32 v10, 31, v6
	v_max_i32_e32 v6, v6, v11
	v_sub_u32_e32 v11, 0, v7
	v_max_i32_e32 v7, v7, v11
	v_cvt_f32_u32_e32 v11, v7
	v_sub_u32_e32 v12, 0, v7
	v_rcp_iflag_f32_e32 v11, v11
	s_nop 0
	v_mul_f32_e32 v11, 0x4f7ffffe, v11
	v_cvt_u32_f32_e32 v11, v11
	v_mul_lo_u32 v12, v12, v11
	v_mul_hi_u32 v12, v11, v12
	v_add_u32_e32 v11, v11, v12
	v_mul_hi_u32 v11, v6, v11
	v_mul_lo_u32 v11, v11, v7
	v_sub_u32_e32 v6, v6, v11
	v_sub_u32_e32 v11, v6, v7
	v_cmp_ge_u32_e32 vcc, v6, v7
	s_nop 1
	v_cndmask_b32_e32 v6, v6, v11, vcc
	v_sub_u32_e32 v11, v6, v7
	v_cmp_ge_u32_e32 vcc, v6, v7
	s_nop 1
	v_cndmask_b32_e32 v6, v6, v11, vcc
	v_xor_b32_e32 v6, v6, v10
	v_sub_u32_e32 v6, v6, v10
	v_add_u32_e32 v6, v9, v6
	v_lshl_or_b32 v6, v6, 8, v1
	v_ashrrev_i32_e32 v7, 31, v6
	v_lshlrev_b64 v[6:7], 6, v[6:7]
	v_lshl_add_u64 v[6:7], s[6:7], 0, v[6:7]
	global_load_dwordx4 v[106:109], v[6:7], off
	global_load_dwordx4 v[110:113], v[6:7], off offset:32
	global_load_dwordx4 v[114:117], v[6:7], off offset:16
	global_load_dwordx4 v[118:121], v[6:7], off offset:48
	v_cmp_le_i32_e32 vcc, s0, v0
	s_or_b64 s[8:9], vcc, s[8:9]
	s_andn2_b64 exec, exec, s[8:9]

.LBB0_1228:
	v_ashrrev_i32_e32 v6, 8, v0
	v_mul_lo_u32 v6, v6, s66
	v_add_u32_e32 v7, s33, v6
	v_ashrrev_i32_e32 v6, 31, v7
	v_lshrrev_b32_e32 v6, 29, v6
	v_add_u32_e32 v9, v7, v6
	v_ashrrev_i32_e32 v6, 3, v9
	v_and_b32_e32 v9, -8, v9
	v_sub_u32_e32 v7, v7, v9
	v_cmp_gt_i32_e32 vcc, 0, v7
	v_add_u32_e32 v0, 0x200, v0
	s_nop 0
	v_cndmask_b32_e32 v9, v3, v4, vcc
	v_mad_u64_u32 v[6:7], s[12:13], v7, v9, v[6:7]
	v_mul_hi_i32 v7, v6, s1
	v_lshrrev_b32_e32 v9, 31, v7
	v_ashrrev_i32_e32 v7, 4, v7
	v_add_u32_e32 v7, v7, v9
	v_lshlrev_b32_e32 v9, 2, v7
	v_mul_lo_u32 v7, v7, s10
	v_sub_u32_e32 v10, 0x80, v9
	v_sub_u32_e32 v6, v6, v7
	v_min_i32_e32 v7, 4, v10
	v_sub_u32_e32 v11, 0, v6
	v_ashrrev_i32_e32 v10, 31, v6
	v_max_i32_e32 v6, v6, v11
	v_sub_u32_e32 v11, 0, v7
	v_max_i32_e32 v7, v7, v11
	v_cvt_f32_u32_e32 v11, v7
	v_sub_u32_e32 v12, 0, v7
	v_rcp_iflag_f32_e32 v11, v11
	s_nop 0
	v_mul_f32_e32 v11, 0x4f7ffffe, v11
	v_cvt_u32_f32_e32 v11, v11
	v_mul_lo_u32 v12, v12, v11
	v_mul_hi_u32 v12, v11, v12
	v_add_u32_e32 v11, v11, v12
	v_mul_hi_u32 v11, v6, v11
	v_mul_lo_u32 v11, v11, v7
	v_sub_u32_e32 v6, v6, v11
	v_sub_u32_e32 v11, v6, v7
	v_cmp_ge_u32_e32 vcc, v6, v7
	s_nop 1
	v_cndmask_b32_e32 v6, v6, v11, vcc
	v_sub_u32_e32 v11, v6, v7
	v_cmp_ge_u32_e32 vcc, v6, v7
	s_nop 1
	v_cndmask_b32_e32 v6, v6, v11, vcc
	v_xor_b32_e32 v6, v6, v10
	v_sub_u32_e32 v6, v6, v10
	v_add_u32_e32 v6, v9, v6
	v_lshl_or_b32 v6, v6, 8, v1
	v_ashrrev_i32_e32 v7, 31, v6
	v_lshlrev_b64 v[6:7], 6, v[6:7]
	v_lshl_add_u64 v[6:7], s[6:7], 0, v[6:7]
	global_load_dwordx4 v[10:13], v[6:7], off
	global_load_dwordx4 v[14:17], v[6:7], off offset:32
	global_load_dwordx4 v[18:21], v[6:7], off offset:16
	global_load_dwordx4 v[22:25], v[6:7], off offset:48
	v_cmp_le_i32_e32 vcc, s0, v0
	s_or_b64 s[8:9], vcc, s[8:9]
	s_waitcnt vmcnt(0)
	v_mov_b32_e32 v6, v10
	v_mov_b32_e32 v7, v14
	v_mov_b32_e32 v14, v11
	v_mov_b32_e32 v10, v12
	v_mov_b32_e32 v11, v16
	v_mov_b32_e32 v16, v13
	v_mov_b32_e32 v12, v18
	v_mov_b32_e32 v13, v22
	v_mov_b32_e32 v22, v19
	v_mov_b32_e32 v18, v20
	v_mov_b32_e32 v19, v24
	v_mov_b32_e32 v24, v21
	v_pk_add_f32 v[6:7], v[6:7], v[14:15]
	v_pk_add_f32 v[10:11], v[10:11], v[16:17]
	v_pk_add_f32 v[12:13], v[12:13], v[22:23]
	v_pk_add_f32 v[14:15], v[18:19], v[24:25]
	v_pk_add_f32 v[6:7], v[6:7], v[10:11]
	v_pk_add_f32 v[10:11], v[12:13], v[14:15]
	s_nop 0
	v_pk_add_f32 v[6:7], v[6:7], v[10:11]
	s_nop 0
	v_add_f32_e32 v6, v6, v7
	v_fmamk_f32 v6, v6, 0x3a800000, v5
	v_rsq_f32_e32 v6, v6
	ds_write_b32 v2, v6
	v_add_u32_e32 v2, 0x800, v2
	s_andn2_b64 exec, exec, s[8:9]
	s_cbranch_execnz .LBB0_1228
; #define PG8_BAR __builtin_amdgcn_s_barrier()
;     __host__ __device__ bool next(int i, Unit& u) const {
;         const long L = (long)i * G + c; if (L >= nwg) return false;
;         int wgid = (int)L; { const int q = nwg / NXCD, r = nwg % NXCD, xcd = wgid % NXCD, off = wgid / NXCD; wgid = (xcd < r ? xcd * (q + 1) : r * (q + 1) + (xcd - r) * q) + off; }
;         const int nig = WGM * nN, gid = wgid / nig, fm = gid * WGM, gsz = (nM - fm) < WGM ? (nM - fm) : WGM;
;         u.pm = fm + ((wgid % nig) % gsz); u.pn = (wgid % nig) / gsz; u.ord = i; return true;
; template <class Epi, class Sched, bool ALIGN_EPI = false, bool SP2 = false>
; __device__ __forceinline__ void gemm_phase(PG8_LAS unsigned char* lds, const Gemm g, const Sched& S, const Epi& E, int tid_in) {
;     ...
;     const int tid = tid_, wid = __builtin_amdgcn_readfirstlane(tid >> 6), lane = tid & 63, wr = wid >> 2, wc = wid & 3, fr = lane & 15, fq = lane >> 4;
;     const int K = g.K, nt = K / BK;
;     unsigned voffA[2], voffB[2];
; #pragma unroll
;     for (int i = 0; i < 2; ++i) { int R, C; stage_rc(tid * 16 + i * 8192, R, C); const int Rb = Epi::PERM ? ((R & ~31) + perm32(R & 31)) : R;
;         voffA[i] = (unsigned)(R * K + C) * 2u; voffB[i] = (unsigned)(Rb * K + C) * 2u; }
;     const size_t kstep = (size_t)(BK * 2);
;     const size_t hstep = (size_t)HALF * K * 2;
;     const size_t tstep = 2 * hstep;
;     const unsigned ldsw = (unsigned)wid * 1024u;
;     const int aoff = lds_byte(wr * 64 + fr, fq * 8), boff = lds_byte(wc * 32 + fr, fq * 8);
;     ...
;     Unit cur, nxt; int ui = 0;
;     if (!S.next(0, cur)) return;
;     f32x4 acc[2][2][4][2];
; #pragma unroll
;     for (int a = 0; a < 2; ++a)
; #pragma unroll
;         for (int b = 0; b < 2; ++b)
; #pragma unroll
;             for (int m = 0; m < 4; ++m)
; #pragma unroll
;                 for (int n = 0; n < 2; ++n) acc[a][b][m][n] = (f32x4){0.f, 0.f, 0.f, 0.f};
;     bf16x8 At[4][2], B0[2][2], B1[2][2];
;     const char* cA = (const char*)g.A + (size_t)cur.pm * tstep; const char* cB = (const char*)g.Bt + (size_t)cur.pn * tstep;
;     S.a_ready(cur);
;     if constexpr (SP2) {
;         PG8_STAGE(PG8_SB(0, 0), cB, voffB); PG8_STAGE(PG8_SB(0, 1), cB + hstep, voffB); PG8_STAGE(PG8_SA(0, 0), cA, voffA); PG8_STAGE(PG8_SA(0, 1), cA + hstep, voffA);
;         if (wr == 1) PG8_BAR;
.LBB0_1229:
	s_or_b64 exec, exec, s[2:3]
	s_waitcnt vmcnt(0) lgkmcnt(0)
	s_barrier
	s_cmpk_gt_i32 s33, 0xaff
	v_readfirstlane_b32 s12, v8
	s_cbranch_scc1 .LBB0_1245
	v_lshlrev_b32_e32 v0, 4, v8
	v_add_u32_e32 v1, 0x2000, v0
	v_ashrrev_i32_e32 v2, 31, v1
	v_lshrrev_b32_e32 v2, 22, v2
	v_add_u32_e32 v2, v1, v2
	v_ashrrev_i32_e32 v9, 10, v2
	v_mul_i32_i24_e32 v2, 0x400, v9
	v_sub_u32_e32 v1, v1, v2
	v_lshrrev_b32_e32 v2, 4, v1
	v_bitop3_b32 v1, v2, v1, 32 bitop3:0x6c
	v_ashrrev_i32_e32 v2, 31, v1
	v_lshrrev_b32_e32 v2, 26, v2
	v_add_u32_e32 v2, v1, v2
	v_lshlrev_b32_e32 v3, 3, v9
	v_ashrrev_i32_e32 v10, 6, v2
	v_and_b32_e32 v3, -16, v3
	v_add_u32_e32 v3, v10, v3
	v_and_b32_e32 v4, 3, v10
	s_mov_b32 s2, 0x1fffe0
	v_lshrrev_b32_e32 v5, 2, v3
	v_lshlrev_b32_e32 v6, 1, v3
	v_and_b32_e32 v2, 0xc0, v2
	v_and_or_b32 v4, v3, s2, v4
	v_and_b32_e32 v5, 4, v5
	v_and_b32_e32 v6, 24, v6
	v_sub_u32_e32 v1, v1, v2
	v_mov_b32_e32 v2, 1
	v_or3_b32 v4, v4, v5, v6
	v_lshlrev_b32_e32 v5, 5, v9
	v_ashrrev_i16_sdwa v1, v2, sext(v1) dst_sel:DWORD dst_unused:UNUSED_PAD src0_sel:DWORD src1_sel:BYTE_0
	v_and_b32_e32 v5, 32, v5
	v_bfe_i32 v11, v1, 0, 16
	v_add_lshl_u32 v1, v5, v11, 1
	v_lshl_add_u32 v128, v4, 11, v1
	v_lshl_add_u32 v130, v3, 11, v1
	v_bfe_i32 v1, v8, 27, 1
	v_lshrrev_b32_e32 v1, 22, v1
	v_add_u32_e32 v1, v0, v1
	v_and_b32_e32 v1, 0xfffffc00, v1
	v_sub_u32_e32 v0, v0, v1
	v_lshrrev_b32_e32 v1, 4, v0
	v_ashrrev_i32_e32 v3, 31, v8
	s_ashr_i32 s8, s12, 6
	v_bitop3_b32 v0, v1, v0, 32 bitop3:0x6c
	v_lshrrev_b32_e32 v3, 26, v3
	s_ashr_i32 s3, s12, 8
	s_lshl_b32 s0, s8, 10
	v_ashrrev_i32_e32 v1, 31, v0
	v_add_u32_e32 v3, v8, v3
	s_add_u32 s1, s40, 0x3a00000
	v_lshrrev_b32_e32 v1, 26, v1
	v_ashrrev_i32_e32 v13, 6, v3
	s_addc_u32 s30, s41, 0
	v_add_u32_e32 v1, v0, v1
	v_lshlrev_b32_e32 v3, 3, v13
	s_add_u32 s31, s40, 0x2000000
	v_ashrrev_i32_e32 v12, 6, v1
	v_and_b32_e32 v3, -16, v3
	s_addc_u32 s34, s41, 0
	v_add_u32_e32 v3, v12, v3
	v_and_b32_e32 v4, 3, v12
	s_ashr_i32 s35, s33, 31
	v_and_or_b32 v4, v3, s2, v4
	s_lshr_b32 s2, s35, 29
	s_add_i32 s2, s33, s2
	s_ashr_i32 s6, s2, 3
	s_and_b32 s2, s2, -8
	s_sub_i32 s2, s33, s2
	s_cmp_lt_i32 s2, 0
	s_movk_i32 s36, 0x161
	s_cselect_b32 s7, s36, 0x160
	s_mul_i32 s2, s2, s7
	s_add_i32 s2, s2, s6
	s_mul_hi_i32 s6, s2, 0x2e8ba2e9
	s_lshr_b32 s7, s6, 31
	s_ashr_i32 s6, s6, 4
	s_add_i32 s6, s6, s7
	s_lshl_b32 s7, s6, 2
	s_mulk_i32 s6, 0x58
	s_sub_i32 s6, s2, s6
	s_sext_i32_i16 s2, s6
	s_bfe_u32 s2, s2, 0x2001c
	s_add_i32 s9, s6, s2
	s_sext_i32_i16 s2, s9
	s_and_b32 s9, s9, 0xfffc
	s_sub_i32 s6, s6, s9
	s_sext_i32_i16 s6, s6
	v_lshrrev_b32_e32 v5, 2, v3
	v_lshlrev_b32_e32 v6, 1, v3
	v_and_b32_e32 v1, 0xc0, v1
	s_lshr_b32 s2, s2, 2
	s_add_i32 s22, s7, s6
	v_and_b32_e32 v5, 4, v5
	v_and_b32_e32 v6, 24, v6
	v_sub_u32_e32 v0, v0, v1
	s_ashr_i32 s23, s22, 31
	s_bfe_i64 s[10:11], s[2:3], 0x100000
	v_or3_b32 v4, v4, v5, v6
	v_lshlrev_b32_e32 v5, 5, v13
	v_ashrrev_i16_sdwa v0, v2, sext(v0) dst_sel:DWORD dst_unused:UNUSED_PAD src0_sel:DWORD src1_sel:BYTE_0
	s_lshl_b64 s[6:7], s[22:23], 19
	s_lshl_b64 s[10:11], s[10:11], 19
	v_and_b32_e32 v5, 32, v5
	v_bfe_i32 v14, v0, 0, 16
	s_add_u32 s26, s31, s10
	v_add_lshl_u32 v0, v5, v14, 1
	s_addc_u32 s27, s34, s11
	s_add_i32 s23, s0, 0
	v_lshl_add_u32 v132, v4, 11, v0
	s_add_i32 m0, s23, 0x10000
	v_lshl_add_u32 v134, v3, 11, v0
	global_load_lds_dwordx4 v132, s[26:27]
	s_add_i32 m0, s23, 0x12000
	s_add_u32 s10, s26, 0x40000
	global_load_lds_dwordx4 v128, s[26:27]
	s_addc_u32 s11, s27, 0
	s_add_i32 m0, s23, 0x14000
	v_mov_b32_e32 v133, 0
	global_load_lds_dwordx4 v132, s[10:11]
	s_add_i32 m0, s23, 0x16000
	s_add_u32 s24, s1, s6
	s_addc_u32 s25, s30, s7
	s_add_i32 s37, s23, 0x2000
	global_load_lds_dwordx4 v128, s[10:11]
	s_mov_b32 m0, s23
	s_add_u32 s6, s24, 0x40000
	global_load_lds_dwordx4 v134, s[24:25]
	s_mov_b32 m0, s37
	s_addc_u32 s7, s25, 0
	s_add_i32 s38, s23, 0x4000
	global_load_lds_dwordx4 v130, s[24:25]
	s_mov_b32 m0, s38
	s_add_i32 s39, s23, 0x6000
	global_load_lds_dwordx4 v134, s[6:7]
	s_mov_b32 m0, s39
	v_mov_b32_e32 v129, v133
	global_load_lds_dwordx4 v130, s[6:7]
	v_mov_b32_e32 v135, v133
	v_mov_b32_e32 v131, v133
	s_cmp_eq_u32 s3, 1
	s_mov_b32 s52, 0
	v_lshl_add_u64 v[6:7], s[26:27], 0, v[132:133]
	v_lshl_add_u64 v[4:5], s[26:27], 0, v[128:129]
	v_lshl_add_u64 v[0:1], s[24:25], 0, v[134:135]
	s_cselect_b64 s[6:7], -1, 0
	s_cmp_lg_u32 s3, 1
	v_lshl_add_u64 v[2:3], s[24:25], 0, v[130:131]
	s_cbranch_scc1 .LBB0_1232
	s_barrier

;     __host__ __device__ bool next(int i, Unit& u) const {
;         const long L = (long)i * G + c; if (L >= nwg) return false;
;         int wgid = (int)L; { const int q = nwg / NXCD, r = nwg % NXCD, xcd = wgid % NXCD, off = wgid / NXCD; wgid = (xcd < r ? xcd * (q + 1) : r * (q + 1) + (xcd - r) * q) + off; }
;         const int nig = WGM * nN, gid = wgid / nig, fm = gid * WGM, gsz = (nM - fm) < WGM ? (nM - fm) : WGM;
;         u.pm = fm + ((wgid % nig) % gsz); u.pn = (wgid % nig) / gsz; u.ord = i; return true;
; template <class Epi, class Sched, bool ALIGN_EPI = false, bool SP2 = false>
; __device__ __forceinline__ void gemm_phase(PG8_LAS unsigned char* lds, const Gemm g, const Sched& S, const Epi& E, int tid_in) {
;     ...
;         const bool has_next = S.next(ui + 1, nxt);
;         const char* nA = has_next ? (const char*)g.A + (size_t)nxt.pm * tstep : cA; const char* nB = has_next ? (const char*)g.Bt + (size_t)nxt.pn * tstep : cB;
.LBB0_1235:
	s_add_i32 s50, s50, 1
	s_mul_i32 s2, s50, s46
	s_mul_hi_u32 s3, s50, s66
	s_add_i32 s3, s3, s2
	s_mul_i32 s2, s50, s66
	s_add_u32 s18, s2, s33
	s_addc_u32 s19, s3, s35
	v_cmp_gt_i64_e32 vcc, s[18:19], v[142:143]
	v_cmp_lt_i64_e64 s[2:3], s[18:19], v[140:141]
	s_cbranch_vccnz .LBB0_1237
	s_ashr_i32 s14, s18, 31
	s_lshr_b32 s14, s14, 29
	s_add_i32 s14, s18, s14
	s_ashr_i32 s15, s14, 3
	s_and_b32 s14, s14, -8
	s_sub_i32 s14, s18, s14
	s_cmp_lt_i32 s14, 0
	s_cselect_b32 s16, s36, 0x160
	s_mul_i32 s14, s14, s16
	s_add_i32 s14, s14, s15
	s_mul_hi_i32 s15, s14, 0x2e8ba2e9
	s_lshr_b32 s16, s15, 31
	s_ashr_i32 s15, s15, 4
	s_add_i32 s15, s15, s16
	s_lshl_b32 s16, s15, 2
	s_sub_i32 s17, 0x80, s16
	s_min_i32 s17, s17, 4
	s_abs_i32 s18, s17
	v_cvt_f32_u32_e32 v0, s18
	s_sub_i32 s20, 0, s18
	s_mulk_i32 s15, 0x58
	s_sub_i32 s15, s14, s15
	v_rcp_iflag_f32_e32 v0, v0
	s_abs_i32 s14, s15
	s_xor_b32 s19, s15, s17
	s_ashr_i32 s19, s19, 31
	v_mul_f32_e32 v0, 0x4f7ffffe, v0
	v_cvt_u32_f32_e32 v0, v0
	s_mov_b32 s51, s50
	v_readfirstlane_b32 s21, v0
	s_mul_i32 s20, s20, s21
	s_mul_hi_u32 s20, s21, s20
	s_add_i32 s21, s21, s20
	s_mul_hi_u32 s20, s14, s21
	s_mul_i32 s21, s20, s18
	s_sub_i32 s14, s14, s21
	s_add_i32 s28, s20, 1
	s_sub_i32 s21, s14, s18
	s_cmp_ge_u32 s14, s18
	s_cselect_b32 s20, s28, s20
	s_cselect_b32 s14, s21, s14
	s_add_i32 s21, s20, 1
	s_cmp_ge_u32 s14, s18
	s_cselect_b32 s14, s21, s20
	s_xor_b32 s14, s14, s19
	s_sub_i32 s14, s14, s19
	s_mul_i32 s17, s14, s17
	s_sub_i32 s15, s15, s17
	s_add_i32 s16, s16, s15
